# last down-projection epilogue rescheduled by hand: residual rows of three row groups kept in flight instead of one 16-byte chunk per wait
# speedup vs baseline: 1.0057x; 1.0008x over previous
.LBB0_2021:
	v_lshl_or_b32 v172, s49, 8, v175
	v_ashrrev_i32_e32 v173, 31, v172
	s_add_u32 s16, s40, s24
	s_addc_u32 s17, s41, s25
	v_lshl_add_u64 v[128:129], v[172:173], 2, s[16:17]
	global_load_dwordx4 v[136:139], v[128:129], off
	global_load_dwordx4 v[140:143], v[128:129], off offset:64
	global_load_dwordx4 v[132:135], v[128:129], off offset:512
	s_nop 0
	global_load_dwordx4 v[128:131], v[128:129], off offset:576
	s_add_u32 s16, s68, s22
	s_addc_u32 s17, s69, s23
	s_and_b64 vcc, exec, s[0:1]
	s_mov_b64 s[0:1], -1
	v_lshl_add_u64 v[252:253], v[148:149], 0, v[172:173]
	v_lshlrev_b64 v[252:253], 2, v[252:253]
	v_lshl_add_u64 v[220:221], s[20:21], 0, v[252:253]
	v_lshl_add_u64 v[222:223], s[16:17], 0, v[252:253]
	global_load_dwordx4 v[188:191], v[220:221], off
	global_load_dwordx4 v[192:195], v[220:221], off offset:64
	global_load_dwordx4 v[196:199], v[220:221], off offset:512
	global_load_dwordx4 v[200:203], v[220:221], off offset:576
	v_lshl_add_u64 v[252:253], v[150:151], 0, v[172:173]
	v_lshlrev_b64 v[252:253], 2, v[252:253]
	v_lshl_add_u64 v[224:225], s[20:21], 0, v[252:253]
	v_lshl_add_u64 v[226:227], s[16:17], 0, v[252:253]
	global_load_dwordx4 v[204:207], v[224:225], off
	global_load_dwordx4 v[208:211], v[224:225], off offset:64
	global_load_dwordx4 v[212:215], v[224:225], off offset:512
	global_load_dwordx4 v[216:219], v[224:225], off offset:576
	v_lshl_add_u64 v[252:253], v[152:153], 0, v[172:173]
	v_lshlrev_b64 v[252:253], 2, v[252:253]
	v_lshl_add_u64 v[248:249], s[20:21], 0, v[252:253]
	v_lshl_add_u64 v[250:251], s[16:17], 0, v[252:253]
	global_load_dwordx4 v[232:235], v[248:249], off
	global_load_dwordx4 v[236:239], v[248:249], off offset:64
	global_load_dwordx4 v[240:243], v[248:249], off offset:512
	global_load_dwordx4 v[244:247], v[248:249], off offset:576
	s_waitcnt vmcnt(11)
	v_pk_fma_f32 v[124:125], v[124:125], v[136:137], v[188:189]
	v_pk_fma_f32 v[126:127], v[126:127], v[138:139], v[190:191]
	s_waitcnt vmcnt(10)
	v_pk_fma_f32 v[120:121], v[120:121], v[140:141], v[192:193]
	v_pk_fma_f32 v[122:123], v[122:123], v[142:143], v[194:195]
	s_waitcnt vmcnt(9)
	v_pk_fma_f32 v[116:117], v[116:117], v[132:133], v[196:197]
	v_pk_fma_f32 v[118:119], v[118:119], v[134:135], v[198:199]
	s_waitcnt vmcnt(8)
	v_pk_fma_f32 v[104:105], v[104:105], v[128:129], v[200:201]
	v_pk_fma_f32 v[106:107], v[106:107], v[130:131], v[202:203]
	global_store_dwordx4 v[222:223], v[124:127], off
	global_store_dwordx4 v[222:223], v[120:123], off offset:64
	global_store_dwordx4 v[222:223], v[116:119], off offset:512
	global_store_dwordx4 v[222:223], v[104:107], off offset:576
	v_lshl_add_u64 v[252:253], v[154:155], 0, v[172:173]
	v_lshlrev_b64 v[252:253], 2, v[252:253]
	v_lshl_add_u64 v[220:221], s[20:21], 0, v[252:253]
	v_lshl_add_u64 v[222:223], s[16:17], 0, v[252:253]
	global_load_dwordx4 v[188:191], v[220:221], off
	global_load_dwordx4 v[192:195], v[220:221], off offset:64
	global_load_dwordx4 v[196:199], v[220:221], off offset:512
	global_load_dwordx4 v[200:203], v[220:221], off offset:576
	s_waitcnt vmcnt(15)
	v_pk_fma_f32 v[112:113], v[112:113], v[136:137], v[204:205]
	v_pk_fma_f32 v[114:115], v[114:115], v[138:139], v[206:207]
	s_waitcnt vmcnt(14)
	v_pk_fma_f32 v[108:109], v[108:109], v[140:141], v[208:209]
	v_pk_fma_f32 v[110:111], v[110:111], v[142:143], v[210:211]
	s_waitcnt vmcnt(13)
	v_pk_fma_f32 v[100:101], v[100:101], v[132:133], v[212:213]
	v_pk_fma_f32 v[102:103], v[102:103], v[134:135], v[214:215]
	s_waitcnt vmcnt(12)
	v_pk_fma_f32 v[88:89], v[88:89], v[128:129], v[216:217]
	v_pk_fma_f32 v[90:91], v[90:91], v[130:131], v[218:219]
	global_store_dwordx4 v[226:227], v[112:115], off
	global_store_dwordx4 v[226:227], v[108:111], off offset:64
	global_store_dwordx4 v[226:227], v[100:103], off offset:512
	global_store_dwordx4 v[226:227], v[88:91], off offset:576
	v_lshl_add_u64 v[252:253], v[156:157], 0, v[172:173]
	v_lshlrev_b64 v[252:253], 2, v[252:253]
	v_lshl_add_u64 v[224:225], s[20:21], 0, v[252:253]
	v_lshl_add_u64 v[226:227], s[16:17], 0, v[252:253]
	global_load_dwordx4 v[204:207], v[224:225], off
	global_load_dwordx4 v[208:211], v[224:225], off offset:64
	global_load_dwordx4 v[212:215], v[224:225], off offset:512
	global_load_dwordx4 v[216:219], v[224:225], off offset:576
	s_waitcnt vmcnt(19)
	v_pk_fma_f32 v[96:97], v[96:97], v[136:137], v[232:233]
	v_pk_fma_f32 v[98:99], v[98:99], v[138:139], v[234:235]
	s_waitcnt vmcnt(18)
	v_pk_fma_f32 v[92:93], v[92:93], v[140:141], v[236:237]
	v_pk_fma_f32 v[94:95], v[94:95], v[142:143], v[238:239]
	s_waitcnt vmcnt(17)
	v_pk_fma_f32 v[84:85], v[84:85], v[132:133], v[240:241]
	v_pk_fma_f32 v[86:87], v[86:87], v[134:135], v[242:243]
	s_waitcnt vmcnt(16)
	v_pk_fma_f32 v[72:73], v[72:73], v[128:129], v[244:245]
	v_pk_fma_f32 v[74:75], v[74:75], v[130:131], v[246:247]
	global_store_dwordx4 v[250:251], v[96:99], off
	global_store_dwordx4 v[250:251], v[92:95], off offset:64
	global_store_dwordx4 v[250:251], v[84:87], off offset:512
	global_store_dwordx4 v[250:251], v[72:75], off offset:576
	v_lshl_add_u64 v[252:253], v[158:159], 0, v[172:173]
	v_lshlrev_b64 v[252:253], 2, v[252:253]
	v_lshl_add_u64 v[248:249], s[20:21], 0, v[252:253]
	v_lshl_add_u64 v[250:251], s[16:17], 0, v[252:253]
	global_load_dwordx4 v[232:235], v[248:249], off
	global_load_dwordx4 v[236:239], v[248:249], off offset:64
	global_load_dwordx4 v[240:243], v[248:249], off offset:512
	global_load_dwordx4 v[244:247], v[248:249], off offset:576
	s_waitcnt vmcnt(19)
	v_pk_fma_f32 v[80:81], v[80:81], v[136:137], v[188:189]
	v_pk_fma_f32 v[82:83], v[82:83], v[138:139], v[190:191]
	s_waitcnt vmcnt(18)
	v_pk_fma_f32 v[76:77], v[76:77], v[140:141], v[192:193]
	v_pk_fma_f32 v[78:79], v[78:79], v[142:143], v[194:195]
	s_waitcnt vmcnt(17)
	v_pk_fma_f32 v[68:69], v[68:69], v[132:133], v[196:197]
	v_pk_fma_f32 v[70:71], v[70:71], v[134:135], v[198:199]
	s_waitcnt vmcnt(16)
	v_pk_fma_f32 v[64:65], v[64:65], v[128:129], v[200:201]
	v_pk_fma_f32 v[66:67], v[66:67], v[130:131], v[202:203]
	global_store_dwordx4 v[222:223], v[80:83], off
	global_store_dwordx4 v[222:223], v[76:79], off offset:64
	global_store_dwordx4 v[222:223], v[68:71], off offset:512
	global_store_dwordx4 v[222:223], v[64:67], off offset:576
	v_lshl_add_u64 v[252:253], v[160:161], 0, v[172:173]
	v_lshlrev_b64 v[252:253], 2, v[252:253]
	v_lshl_add_u64 v[220:221], s[20:21], 0, v[252:253]
	v_lshl_add_u64 v[222:223], s[16:17], 0, v[252:253]
	global_load_dwordx4 v[188:191], v[220:221], off
	global_load_dwordx4 v[192:195], v[220:221], off offset:64
	global_load_dwordx4 v[196:199], v[220:221], off offset:512
	global_load_dwordx4 v[200:203], v[220:221], off offset:576
	s_waitcnt vmcnt(19)
	v_pk_fma_f32 v[60:61], v[60:61], v[136:137], v[204:205]
	v_pk_fma_f32 v[62:63], v[62:63], v[138:139], v[206:207]
	s_waitcnt vmcnt(18)
	v_pk_fma_f32 v[56:57], v[56:57], v[140:141], v[208:209]
	v_pk_fma_f32 v[58:59], v[58:59], v[142:143], v[210:211]
	s_waitcnt vmcnt(17)
	v_pk_fma_f32 v[52:53], v[52:53], v[132:133], v[212:213]
	v_pk_fma_f32 v[54:55], v[54:55], v[134:135], v[214:215]
	s_waitcnt vmcnt(16)
	v_pk_fma_f32 v[40:41], v[40:41], v[128:129], v[216:217]
	v_pk_fma_f32 v[42:43], v[42:43], v[130:131], v[218:219]
	global_store_dwordx4 v[226:227], v[60:63], off
	global_store_dwordx4 v[226:227], v[56:59], off offset:64
	global_store_dwordx4 v[226:227], v[52:55], off offset:512
	global_store_dwordx4 v[226:227], v[40:43], off offset:576
	v_lshl_add_u64 v[252:253], v[162:163], 0, v[172:173]
	v_lshlrev_b64 v[252:253], 2, v[252:253]
	v_lshl_add_u64 v[224:225], s[20:21], 0, v[252:253]
	v_lshl_add_u64 v[226:227], s[16:17], 0, v[252:253]
	global_load_dwordx4 v[204:207], v[224:225], off
	global_load_dwordx4 v[208:211], v[224:225], off offset:64
	global_load_dwordx4 v[212:215], v[224:225], off offset:512
	global_load_dwordx4 v[216:219], v[224:225], off offset:576
	s_waitcnt vmcnt(19)
	v_pk_fma_f32 v[48:49], v[48:49], v[136:137], v[232:233]
	v_pk_fma_f32 v[50:51], v[50:51], v[138:139], v[234:235]
	s_waitcnt vmcnt(18)
	v_pk_fma_f32 v[44:45], v[44:45], v[140:141], v[236:237]
	v_pk_fma_f32 v[46:47], v[46:47], v[142:143], v[238:239]
	s_waitcnt vmcnt(17)
	v_pk_fma_f32 v[36:37], v[36:37], v[132:133], v[240:241]
	v_pk_fma_f32 v[38:39], v[38:39], v[134:135], v[242:243]
	s_waitcnt vmcnt(16)
	v_pk_fma_f32 v[24:25], v[24:25], v[128:129], v[244:245]
	v_pk_fma_f32 v[26:27], v[26:27], v[130:131], v[246:247]
	global_store_dwordx4 v[250:251], v[48:51], off
	global_store_dwordx4 v[250:251], v[44:47], off offset:64
	global_store_dwordx4 v[250:251], v[36:39], off offset:512
	global_store_dwordx4 v[250:251], v[24:27], off offset:576
	s_waitcnt vmcnt(15)
	v_pk_fma_f32 v[32:33], v[32:33], v[136:137], v[188:189]
	v_pk_fma_f32 v[34:35], v[34:35], v[138:139], v[190:191]
	s_waitcnt vmcnt(14)
	v_pk_fma_f32 v[28:29], v[28:29], v[140:141], v[192:193]
	v_pk_fma_f32 v[30:31], v[30:31], v[142:143], v[194:195]
	s_waitcnt vmcnt(13)
	v_pk_fma_f32 v[20:21], v[20:21], v[132:133], v[196:197]
	v_pk_fma_f32 v[22:23], v[22:23], v[134:135], v[198:199]
	s_waitcnt vmcnt(12)
	v_pk_fma_f32 v[8:9], v[8:9], v[128:129], v[200:201]
	v_pk_fma_f32 v[10:11], v[10:11], v[130:131], v[202:203]
	global_store_dwordx4 v[222:223], v[32:35], off
	global_store_dwordx4 v[222:223], v[28:31], off offset:64
	global_store_dwordx4 v[222:223], v[20:23], off offset:512
	global_store_dwordx4 v[222:223], v[8:11], off offset:576
	s_waitcnt vmcnt(11)
	v_pk_fma_f32 v[16:17], v[16:17], v[136:137], v[204:205]
	v_pk_fma_f32 v[18:19], v[18:19], v[138:139], v[206:207]
	s_waitcnt vmcnt(10)
	v_pk_fma_f32 v[12:13], v[12:13], v[140:141], v[208:209]
	v_pk_fma_f32 v[14:15], v[14:15], v[142:143], v[210:211]
	s_waitcnt vmcnt(9)
	v_pk_fma_f32 v[4:5], v[4:5], v[132:133], v[212:213]
	v_pk_fma_f32 v[6:7], v[6:7], v[134:135], v[214:215]
	s_waitcnt vmcnt(8)
	v_pk_fma_f32 v[0:1], v[0:1], v[128:129], v[216:217]
	v_pk_fma_f32 v[2:3], v[2:3], v[130:131], v[218:219]
	global_store_dwordx4 v[226:227], v[16:19], off
	global_store_dwordx4 v[226:227], v[12:15], off offset:64
	global_store_dwordx4 v[226:227], v[4:7], off offset:512
	global_store_dwordx4 v[226:227], v[0:3], off offset:576
	s_cbranch_vccnz .LBB0_2002
	s_andn2_b64 vcc, exec, s[8:9]
	s_cbranch_vccnz .LBB0_2001
	s_barrier
	s_branch .LBB0_2001
